# mixer queue: next index prefetched by thread 0 under the attention unit's epilogue; context attention units popped in (map 0, map 1) pairs
# baseline (speedup 1.0000x reference)
.LBB0_521:
	s_mov_b32 s0, s93
	v_readlane_b32 s4, v253, 54
	v_mbcnt_lo_u32_b32 v0, -1, s0
	v_mbcnt_hi_u32_b32 v0, -1, v0
	v_or_b32_e32 v0, s84, v0
	s_mov_b32 s0, s88
	v_readlane_b32 s6, v253, 56
	v_readlane_b32 s0, v254, 52
	v_readlane_b32 s8, v253, 58
	v_readlane_b32 s1, v254, 53
	s_lshl_b32 s92, s0, 6
	s_mov_b32 s8, s0
	s_lshl_b64 s[0:1], s[92:93], 2
	v_readlane_b32 s6, v253, 20
	v_readlane_b32 s62, v253, 0
	s_add_u32 s66, s6, s0
	v_readlane_b32 s0, v253, 21
	v_readlane_b32 s63, v253, 1
	s_addc_u32 s67, s0, s1
	s_and_b32 s0, s88, 7
	s_lshl_b32 s0, s0, 8
	s_mul_i32 s1, s8, 0x700
	s_add_i32 s0, s0, s1
	s_add_i32 s0, s0, 0xf000
	v_writelane_b32 v251, 0, 20
	s_add_u32 s66, s66, s0
	s_addc_u32 s67, s67, 0
	s_add_u32 s40, s62, 0x18b00000
	s_addc_u32 s41, s63, 0
	s_add_u32 s42, s62, 0x1bb00000
	s_addc_u32 s43, s63, 0
	s_add_u32 s44, s62, 0x1ed00000
	s_addc_u32 s45, s63, 0
	s_add_u32 s48, s62, 0x3cf00000
	s_addc_u32 s49, s63, 0
	s_lshl_b32 s52, s8, 2
	s_add_u32 s53, s62, 0x2df00000
	s_addc_u32 s58, s63, 0
	s_add_u32 s59, s62, 0x30f00000
	s_addc_u32 s80, s63, 0
	s_add_u32 s81, s62, 0x200000
	s_addc_u32 s68, s63, 0
	v_readlane_b32 s5, v253, 55
	v_readlane_b32 s18, v254, 4
	v_readlane_b32 s19, v254, 5
	s_add_u32 s54, s62, 0x12b00000
	s_mov_b32 s96, 0x10000
	s_mov_b32 s91, 0x30000
	s_mov_b64 s[64:65], s[18:19]
	v_cmp_eq_u32_e64 s[4:5], 0, v0
	s_addc_u32 s55, s63, 0
	v_readlane_b32 s7, v253, 57
	v_readlane_b32 s9, v253, 59
	v_readlane_b32 s10, v253, 60
	v_readlane_b32 s11, v253, 61
	v_readlane_b32 s12, v253, 62
	v_readlane_b32 s13, v253, 63
	v_readlane_b32 s14, v254, 0
	v_readlane_b32 s15, v254, 1
	v_readlane_b32 s16, v254, 2
	v_readlane_b32 s17, v254, 3
	s_branch .LBB0_524

.LBB0_524:
	s_and_saveexec_b64 s[6:7], s[4:5]
	s_cbranch_execz .LBB0_528
	s_mov_b64 s[10:11], exec
	v_mbcnt_lo_u32_b32 v0, s10, 0
	v_mbcnt_hi_u32_b32 v0, s11, v0
	v_cmp_eq_u32_e32 vcc, 0, v0
	s_and_saveexec_b64 s[8:9], vcc
	s_cbranch_execz .LBB0_527
	v_readlane_b32 s0, v251, 20
	s_cmp_eq_u32 s0, 0
	s_cbranch_scc1 .Lq_nopf
	v_writelane_b32 v251, 0, 20
	s_waitcnt vmcnt(0)
	v_mov_b32_e32 v1, v249
	s_branch .LBB0_527
.Lq_nopf:
	s_bcnt1_i32_b64 s0, s[10:11]
	v_mov_b32_e32 v1, s0
	global_atomic_add v1, v97, v1, s[66:67] sc0

.LBB0_528:
	s_or_b64 exec, exec, s[6:7]
	v_mov_b32_e32 v0, s31
	s_waitcnt vmcnt(0) lgkmcnt(0)
	s_barrier
	ds_read_b32 v0, v0
	s_movk_i32 s1, 0x51f
	s_mov_b64 s[6:7], -1
	s_waitcnt lgkmcnt(0)
	s_barrier
	v_readfirstlane_b32 s0, v0
	s_and_b32 s1, s88, 7
	s_cmpk_gt_u32 s0, 0x83
	s_cbranch_scc1 .LBB0_523
	s_cmp_lt_u32 s0, 4
	s_cbranch_scc1 .Lq_chain
	s_cmp_lt_u32 s0, 36
	s_cbranch_scc1 .Lq_lat
	s_lshl_b32 s1, s1, 6
	s_cmpk_lt_u32 s0, 0x64
	s_cbranch_scc1 .Lq_scan
	s_lshl_b32 s0, s0, 1
	s_add_i32 s0, s0, 0x258
	s_add_i32 s0, s0, s1
	s_branch .Lq_done
.Lq_scan:
	s_add_i32 s0, s0, 0xfc
	s_add_i32 s0, s0, s1
	s_branch .Lq_done

.Lam_unit:
	s_lshl_b32 s46, s0, 1
	s_cmpk_lt_u32 s0, 0x120
	s_cselect_b32 s8, 64, 0x440
	s_sub_i32 s46, s46, s8
	s_cmpk_gt_u32 s46, 0x1ff
	s_cbranch_scc1 .Lam_ctx
	s_lshr_b32 s8, s46, 8
	s_bfe_u32 s9, s46, 0x30002
	s_lshl_b32 s10, s8, 11
	s_lshl_b32 s9, s9, 8
	s_add_i32 s10, s10, s9
	s_add_i32 s10, s10, 0x2000
	s_mulk_i32 s8, 0x900
	s_add_i32 s11, s8, 0x2000
	s_bfe_u32 s12, s46, 0x30005
	s_mov_b32 s13, 36
	s_branch .Lam_go

.Lam_nodma_b:
	s_sub_i32 s13, s13, 2
	s_cmp_gt_u32 s13, 0
	s_cbranch_scc1 .Lam_loop
	s_cmpk_lt_u32 s0, 0x320
	s_cbranch_scc1 .Lam_pf
	s_bitcmp1_b32 s0, 0
	s_cbranch_scc0 .Lam_nopf
.Lam_pf:
	s_mov_b64 s[8:9], exec
	s_and_b64 exec, exec, s[4:5]
	s_cbranch_execz .Lam_pfx
	v_mov_b32_e32 v249, 1
	global_atomic_add v249, v97, v249, s[66:67] sc0
.Lam_pfx:
	s_mov_b64 exec, s[8:9]
	v_writelane_b32 v251, 1, 20
.Lam_nopf:
	v_and_b32_e32 v240, 31, v96
	v_lshl_add_u32 v241, v240, 2, s50
	ds_write_b32 v241, v239 offset:128
	v_lshrrev_b32_e32 v241, 5, v96
	v_lshl_add_u32 v242, v241, 4, s50
	s_waitcnt lgkmcnt(0)
	ds_read_b128 v[212:215], v242 offset:128
	ds_read_b128 v[216:219], v242 offset:160
	ds_read_b128 v[220:223], v242 offset:192
	ds_read_b128 v[224:227], v242 offset:224
	s_lshl_b32 s37, s36, 5
	v_lshl_add_u32 v241, v241, 2, s37
	v_lshlrev_b32_e32 v241, 13, v241
	v_lshl_add_u32 v241, v240, 1, v241
	s_waitcnt lgkmcnt(0)
	v_rcp_f32_e32 v212, v212
	v_rcp_f32_e32 v213, v213
	v_rcp_f32_e32 v214, v214
	v_rcp_f32_e32 v215, v215
	v_rcp_f32_e32 v216, v216
	v_rcp_f32_e32 v217, v217
	v_rcp_f32_e32 v218, v218
	v_rcp_f32_e32 v219, v219
	v_rcp_f32_e32 v220, v220
	v_rcp_f32_e32 v221, v221
	v_rcp_f32_e32 v222, v222
	v_rcp_f32_e32 v223, v223
	v_rcp_f32_e32 v224, v224
	v_rcp_f32_e32 v225, v225
	v_rcp_f32_e32 v226, v226
	v_rcp_f32_e32 v227, v227
	s_nop 0
	v_mov_b32_e32 v240, v241
	v_mul_f32_e32 v162, v0, v212
	v_cvt_pk_bf16_f32 v162, v162, v162
	global_store_short v240, v162, s[22:23]
	v_mul_f32_e32 v163, v16, v212
	v_cvt_pk_bf16_f32 v163, v163, v163
	global_store_short v240, v163, s[22:23] offset:64
	v_mul_f32_e32 v164, v32, v212
	v_cvt_pk_bf16_f32 v164, v164, v164
	global_store_short v240, v164, s[22:23] offset:128
	v_mul_f32_e32 v165, v48, v212
	v_cvt_pk_bf16_f32 v165, v165, v165
	global_store_short v240, v165, s[22:23] offset:192
	v_mul_f32_e32 v166, v64, v212
	v_cvt_pk_bf16_f32 v166, v166, v166
	global_store_short v240, v166, s[22:23] offset:256
	v_mul_f32_e32 v167, v80, v212
	v_cvt_pk_bf16_f32 v167, v167, v167
	global_store_short v240, v167, s[22:23] offset:320
	v_mul_f32_e32 v168, v98, v212
	v_cvt_pk_bf16_f32 v168, v168, v168
	global_store_short v240, v168, s[22:23] offset:384
	v_mul_f32_e32 v169, v114, v212
	v_cvt_pk_bf16_f32 v169, v169, v169
	global_store_short v240, v169, s[22:23] offset:448
	v_add_u32_e32 v240, 0x2000, v241
	v_mul_f32_e32 v170, v1, v213
	v_cvt_pk_bf16_f32 v170, v170, v170
	global_store_short v240, v170, s[22:23]
	v_mul_f32_e32 v171, v17, v213
	v_cvt_pk_bf16_f32 v171, v171, v171
	global_store_short v240, v171, s[22:23] offset:64
	v_mul_f32_e32 v172, v33, v213
	v_cvt_pk_bf16_f32 v172, v172, v172
	global_store_short v240, v172, s[22:23] offset:128
	v_mul_f32_e32 v173, v49, v213
	v_cvt_pk_bf16_f32 v173, v173, v173
	global_store_short v240, v173, s[22:23] offset:192
	v_mul_f32_e32 v174, v65, v213
	v_cvt_pk_bf16_f32 v174, v174, v174
	global_store_short v240, v174, s[22:23] offset:256
	v_mul_f32_e32 v175, v81, v213
	v_cvt_pk_bf16_f32 v175, v175, v175
	global_store_short v240, v175, s[22:23] offset:320
	v_mul_f32_e32 v176, v99, v213
	v_cvt_pk_bf16_f32 v176, v176, v176
	global_store_short v240, v176, s[22:23] offset:384
	v_mul_f32_e32 v177, v115, v213
	v_cvt_pk_bf16_f32 v177, v177, v177
	global_store_short v240, v177, s[22:23] offset:448
	v_add_u32_e32 v240, 0x4000, v241
	v_mul_f32_e32 v178, v2, v214
	v_cvt_pk_bf16_f32 v178, v178, v178
	global_store_short v240, v178, s[22:23]
	v_mul_f32_e32 v179, v18, v214
	v_cvt_pk_bf16_f32 v179, v179, v179
	global_store_short v240, v179, s[22:23] offset:64
	v_mul_f32_e32 v180, v34, v214
	v_cvt_pk_bf16_f32 v180, v180, v180
	global_store_short v240, v180, s[22:23] offset:128
	v_mul_f32_e32 v181, v50, v214
	v_cvt_pk_bf16_f32 v181, v181, v181
	global_store_short v240, v181, s[22:23] offset:192
	v_mul_f32_e32 v182, v66, v214
	v_cvt_pk_bf16_f32 v182, v182, v182
	global_store_short v240, v182, s[22:23] offset:256
	v_mul_f32_e32 v183, v82, v214
	v_cvt_pk_bf16_f32 v183, v183, v183
	global_store_short v240, v183, s[22:23] offset:320
	v_mul_f32_e32 v184, v100, v214
	v_cvt_pk_bf16_f32 v184, v184, v184
	global_store_short v240, v184, s[22:23] offset:384
	v_mul_f32_e32 v185, v116, v214
	v_cvt_pk_bf16_f32 v185, v185, v185
	global_store_short v240, v185, s[22:23] offset:448
	v_add_u32_e32 v240, 0x6000, v241
	v_mul_f32_e32 v186, v3, v215
	v_cvt_pk_bf16_f32 v186, v186, v186
	global_store_short v240, v186, s[22:23]
	v_mul_f32_e32 v187, v19, v215
	v_cvt_pk_bf16_f32 v187, v187, v187
	global_store_short v240, v187, s[22:23] offset:64
	v_mul_f32_e32 v188, v35, v215
	v_cvt_pk_bf16_f32 v188, v188, v188
	global_store_short v240, v188, s[22:23] offset:128
	v_mul_f32_e32 v189, v51, v215
	v_cvt_pk_bf16_f32 v189, v189, v189
	global_store_short v240, v189, s[22:23] offset:192
	v_mul_f32_e32 v190, v67, v215
	v_cvt_pk_bf16_f32 v190, v190, v190
	global_store_short v240, v190, s[22:23] offset:256
	v_mul_f32_e32 v191, v83, v215
	v_cvt_pk_bf16_f32 v191, v191, v191
	global_store_short v240, v191, s[22:23] offset:320
	v_mul_f32_e32 v192, v101, v215
	v_cvt_pk_bf16_f32 v192, v192, v192
	global_store_short v240, v192, s[22:23] offset:384
	v_mul_f32_e32 v193, v117, v215
	v_cvt_pk_bf16_f32 v193, v193, v193
	global_store_short v240, v193, s[22:23] offset:448
	v_add_u32_e32 v240, 0x10000, v241
	v_mul_f32_e32 v162, v4, v216
	v_cvt_pk_bf16_f32 v162, v162, v162
	global_store_short v240, v162, s[22:23]
	v_mul_f32_e32 v163, v20, v216
	v_cvt_pk_bf16_f32 v163, v163, v163
	global_store_short v240, v163, s[22:23] offset:64
	v_mul_f32_e32 v164, v36, v216
	v_cvt_pk_bf16_f32 v164, v164, v164
	global_store_short v240, v164, s[22:23] offset:128
	v_mul_f32_e32 v165, v52, v216
	v_cvt_pk_bf16_f32 v165, v165, v165
	global_store_short v240, v165, s[22:23] offset:192
	v_mul_f32_e32 v166, v68, v216
	v_cvt_pk_bf16_f32 v166, v166, v166
	global_store_short v240, v166, s[22:23] offset:256
	v_mul_f32_e32 v167, v84, v216
	v_cvt_pk_bf16_f32 v167, v167, v167
	global_store_short v240, v167, s[22:23] offset:320
	v_mul_f32_e32 v168, v102, v216
	v_cvt_pk_bf16_f32 v168, v168, v168
	global_store_short v240, v168, s[22:23] offset:384
	v_mul_f32_e32 v169, v118, v216
	v_cvt_pk_bf16_f32 v169, v169, v169
	global_store_short v240, v169, s[22:23] offset:448
	v_add_u32_e32 v240, 0x12000, v241
	v_mul_f32_e32 v170, v5, v217
	v_cvt_pk_bf16_f32 v170, v170, v170
	global_store_short v240, v170, s[22:23]
	v_mul_f32_e32 v171, v21, v217
	v_cvt_pk_bf16_f32 v171, v171, v171
	global_store_short v240, v171, s[22:23] offset:64
	v_mul_f32_e32 v172, v37, v217
	v_cvt_pk_bf16_f32 v172, v172, v172
	global_store_short v240, v172, s[22:23] offset:128
	v_mul_f32_e32 v173, v53, v217
	v_cvt_pk_bf16_f32 v173, v173, v173
	global_store_short v240, v173, s[22:23] offset:192
	v_mul_f32_e32 v174, v69, v217
	v_cvt_pk_bf16_f32 v174, v174, v174
	global_store_short v240, v174, s[22:23] offset:256
	v_mul_f32_e32 v175, v85, v217
	v_cvt_pk_bf16_f32 v175, v175, v175
	global_store_short v240, v175, s[22:23] offset:320
	v_mul_f32_e32 v176, v103, v217
	v_cvt_pk_bf16_f32 v176, v176, v176
	global_store_short v240, v176, s[22:23] offset:384
	v_mul_f32_e32 v177, v119, v217
	v_cvt_pk_bf16_f32 v177, v177, v177
	global_store_short v240, v177, s[22:23] offset:448
	v_add_u32_e32 v240, 0x14000, v241
	v_mul_f32_e32 v178, v6, v218
	v_cvt_pk_bf16_f32 v178, v178, v178
	global_store_short v240, v178, s[22:23]
	v_mul_f32_e32 v179, v22, v218
	v_cvt_pk_bf16_f32 v179, v179, v179
	global_store_short v240, v179, s[22:23] offset:64
	v_mul_f32_e32 v180, v38, v218
	v_cvt_pk_bf16_f32 v180, v180, v180
	global_store_short v240, v180, s[22:23] offset:128
	v_mul_f32_e32 v181, v54, v218
	v_cvt_pk_bf16_f32 v181, v181, v181
	global_store_short v240, v181, s[22:23] offset:192
	v_mul_f32_e32 v182, v70, v218
	v_cvt_pk_bf16_f32 v182, v182, v182
	global_store_short v240, v182, s[22:23] offset:256
	v_mul_f32_e32 v183, v86, v218
	v_cvt_pk_bf16_f32 v183, v183, v183
	global_store_short v240, v183, s[22:23] offset:320
	v_mul_f32_e32 v184, v104, v218
	v_cvt_pk_bf16_f32 v184, v184, v184
	global_store_short v240, v184, s[22:23] offset:384
	v_mul_f32_e32 v185, v120, v218
	v_cvt_pk_bf16_f32 v185, v185, v185
	global_store_short v240, v185, s[22:23] offset:448
	v_add_u32_e32 v240, 0x16000, v241
	v_mul_f32_e32 v186, v7, v219
	v_cvt_pk_bf16_f32 v186, v186, v186
	global_store_short v240, v186, s[22:23]
	v_mul_f32_e32 v187, v23, v219
	v_cvt_pk_bf16_f32 v187, v187, v187
	global_store_short v240, v187, s[22:23] offset:64
	v_mul_f32_e32 v188, v39, v219
	v_cvt_pk_bf16_f32 v188, v188, v188
	global_store_short v240, v188, s[22:23] offset:128
	v_mul_f32_e32 v189, v55, v219
	v_cvt_pk_bf16_f32 v189, v189, v189
	global_store_short v240, v189, s[22:23] offset:192
	v_mul_f32_e32 v190, v71, v219
	v_cvt_pk_bf16_f32 v190, v190, v190
	global_store_short v240, v190, s[22:23] offset:256
	v_mul_f32_e32 v191, v87, v219
	v_cvt_pk_bf16_f32 v191, v191, v191
	global_store_short v240, v191, s[22:23] offset:320
	v_mul_f32_e32 v192, v105, v219
	v_cvt_pk_bf16_f32 v192, v192, v192
	global_store_short v240, v192, s[22:23] offset:384
	v_mul_f32_e32 v193, v121, v219
	v_cvt_pk_bf16_f32 v193, v193, v193
	global_store_short v240, v193, s[22:23] offset:448
	v_add_u32_e32 v240, 0x20000, v241
	v_mul_f32_e32 v162, v8, v220
	v_cvt_pk_bf16_f32 v162, v162, v162
	global_store_short v240, v162, s[22:23]
	v_mul_f32_e32 v163, v24, v220
	v_cvt_pk_bf16_f32 v163, v163, v163
	global_store_short v240, v163, s[22:23] offset:64
	v_mul_f32_e32 v164, v40, v220
	v_cvt_pk_bf16_f32 v164, v164, v164
	global_store_short v240, v164, s[22:23] offset:128
	v_mul_f32_e32 v165, v56, v220
	v_cvt_pk_bf16_f32 v165, v165, v165
	global_store_short v240, v165, s[22:23] offset:192
	v_mul_f32_e32 v166, v72, v220
	v_cvt_pk_bf16_f32 v166, v166, v166
	global_store_short v240, v166, s[22:23] offset:256
	v_mul_f32_e32 v167, v88, v220
	v_cvt_pk_bf16_f32 v167, v167, v167
	global_store_short v240, v167, s[22:23] offset:320
	v_mul_f32_e32 v168, v106, v220
	v_cvt_pk_bf16_f32 v168, v168, v168
	global_store_short v240, v168, s[22:23] offset:384
	v_mul_f32_e32 v169, v122, v220
	v_cvt_pk_bf16_f32 v169, v169, v169
	global_store_short v240, v169, s[22:23] offset:448
	v_add_u32_e32 v240, 0x22000, v241
	v_mul_f32_e32 v170, v9, v221
	v_cvt_pk_bf16_f32 v170, v170, v170
	global_store_short v240, v170, s[22:23]
	v_mul_f32_e32 v171, v25, v221
	v_cvt_pk_bf16_f32 v171, v171, v171
	global_store_short v240, v171, s[22:23] offset:64
	v_mul_f32_e32 v172, v41, v221
	v_cvt_pk_bf16_f32 v172, v172, v172
	global_store_short v240, v172, s[22:23] offset:128
	v_mul_f32_e32 v173, v57, v221
	v_cvt_pk_bf16_f32 v173, v173, v173
	global_store_short v240, v173, s[22:23] offset:192
	v_mul_f32_e32 v174, v73, v221
	v_cvt_pk_bf16_f32 v174, v174, v174
	global_store_short v240, v174, s[22:23] offset:256
	v_mul_f32_e32 v175, v89, v221
	v_cvt_pk_bf16_f32 v175, v175, v175
	global_store_short v240, v175, s[22:23] offset:320
	v_mul_f32_e32 v176, v107, v221
	v_cvt_pk_bf16_f32 v176, v176, v176
	global_store_short v240, v176, s[22:23] offset:384
	v_mul_f32_e32 v177, v123, v221
	v_cvt_pk_bf16_f32 v177, v177, v177
	global_store_short v240, v177, s[22:23] offset:448
	v_add_u32_e32 v240, 0x24000, v241
	v_mul_f32_e32 v178, v10, v222
	v_cvt_pk_bf16_f32 v178, v178, v178
	global_store_short v240, v178, s[22:23]
	v_mul_f32_e32 v179, v26, v222
	v_cvt_pk_bf16_f32 v179, v179, v179
	global_store_short v240, v179, s[22:23] offset:64
	v_mul_f32_e32 v180, v42, v222
	v_cvt_pk_bf16_f32 v180, v180, v180
	global_store_short v240, v180, s[22:23] offset:128
	v_mul_f32_e32 v181, v58, v222
	v_cvt_pk_bf16_f32 v181, v181, v181
	global_store_short v240, v181, s[22:23] offset:192
	v_mul_f32_e32 v182, v74, v222
	v_cvt_pk_bf16_f32 v182, v182, v182
	global_store_short v240, v182, s[22:23] offset:256
	v_mul_f32_e32 v183, v90, v222
	v_cvt_pk_bf16_f32 v183, v183, v183
	global_store_short v240, v183, s[22:23] offset:320
	v_mul_f32_e32 v184, v108, v222
	v_cvt_pk_bf16_f32 v184, v184, v184
	global_store_short v240, v184, s[22:23] offset:384
	v_mul_f32_e32 v185, v124, v222
	v_cvt_pk_bf16_f32 v185, v185, v185
	global_store_short v240, v185, s[22:23] offset:448
	v_add_u32_e32 v240, 0x26000, v241
	v_mul_f32_e32 v186, v11, v223
	v_cvt_pk_bf16_f32 v186, v186, v186
	global_store_short v240, v186, s[22:23]
	v_mul_f32_e32 v187, v27, v223
	v_cvt_pk_bf16_f32 v187, v187, v187
	global_store_short v240, v187, s[22:23] offset:64
	v_mul_f32_e32 v188, v43, v223
	v_cvt_pk_bf16_f32 v188, v188, v188
	global_store_short v240, v188, s[22:23] offset:128
	v_mul_f32_e32 v189, v59, v223
	v_cvt_pk_bf16_f32 v189, v189, v189
	global_store_short v240, v189, s[22:23] offset:192
	v_mul_f32_e32 v190, v75, v223
	v_cvt_pk_bf16_f32 v190, v190, v190
	global_store_short v240, v190, s[22:23] offset:256
	v_mul_f32_e32 v191, v91, v223
	v_cvt_pk_bf16_f32 v191, v191, v191
	global_store_short v240, v191, s[22:23] offset:320
	v_mul_f32_e32 v192, v109, v223
	v_cvt_pk_bf16_f32 v192, v192, v192
	global_store_short v240, v192, s[22:23] offset:384
	v_mul_f32_e32 v193, v125, v223
	v_cvt_pk_bf16_f32 v193, v193, v193
	global_store_short v240, v193, s[22:23] offset:448
	v_add_u32_e32 v240, 0x30000, v241
	v_mul_f32_e32 v162, v12, v224
	v_cvt_pk_bf16_f32 v162, v162, v162
	global_store_short v240, v162, s[22:23]
	v_mul_f32_e32 v163, v28, v224
	v_cvt_pk_bf16_f32 v163, v163, v163
	global_store_short v240, v163, s[22:23] offset:64
	v_mul_f32_e32 v164, v44, v224
	v_cvt_pk_bf16_f32 v164, v164, v164
	global_store_short v240, v164, s[22:23] offset:128
	v_mul_f32_e32 v165, v60, v224
	v_cvt_pk_bf16_f32 v165, v165, v165
	global_store_short v240, v165, s[22:23] offset:192
	v_mul_f32_e32 v166, v76, v224
	v_cvt_pk_bf16_f32 v166, v166, v166
	global_store_short v240, v166, s[22:23] offset:256
	v_mul_f32_e32 v167, v92, v224
	v_cvt_pk_bf16_f32 v167, v167, v167
	global_store_short v240, v167, s[22:23] offset:320
	v_mul_f32_e32 v168, v110, v224
	v_cvt_pk_bf16_f32 v168, v168, v168
	global_store_short v240, v168, s[22:23] offset:384
	v_mul_f32_e32 v169, v126, v224
	v_cvt_pk_bf16_f32 v169, v169, v169
	global_store_short v240, v169, s[22:23] offset:448
	v_add_u32_e32 v240, 0x32000, v241
	v_mul_f32_e32 v170, v13, v225
	v_cvt_pk_bf16_f32 v170, v170, v170
	global_store_short v240, v170, s[22:23]
	v_mul_f32_e32 v171, v29, v225
	v_cvt_pk_bf16_f32 v171, v171, v171
	global_store_short v240, v171, s[22:23] offset:64
	v_mul_f32_e32 v172, v45, v225
	v_cvt_pk_bf16_f32 v172, v172, v172
	global_store_short v240, v172, s[22:23] offset:128
	v_mul_f32_e32 v173, v61, v225
	v_cvt_pk_bf16_f32 v173, v173, v173
	global_store_short v240, v173, s[22:23] offset:192
	v_mul_f32_e32 v174, v77, v225
	v_cvt_pk_bf16_f32 v174, v174, v174
	global_store_short v240, v174, s[22:23] offset:256
	v_mul_f32_e32 v175, v93, v225
	v_cvt_pk_bf16_f32 v175, v175, v175
	global_store_short v240, v175, s[22:23] offset:320
	v_mul_f32_e32 v176, v111, v225
	v_cvt_pk_bf16_f32 v176, v176, v176
	global_store_short v240, v176, s[22:23] offset:384
	v_mul_f32_e32 v177, v127, v225
	v_cvt_pk_bf16_f32 v177, v177, v177
	global_store_short v240, v177, s[22:23] offset:448
	v_add_u32_e32 v240, 0x34000, v241
	v_mul_f32_e32 v178, v14, v226
	v_cvt_pk_bf16_f32 v178, v178, v178
	global_store_short v240, v178, s[22:23]
	v_mul_f32_e32 v179, v30, v226
	v_cvt_pk_bf16_f32 v179, v179, v179
	global_store_short v240, v179, s[22:23] offset:64
	v_mul_f32_e32 v180, v46, v226
	v_cvt_pk_bf16_f32 v180, v180, v180
	global_store_short v240, v180, s[22:23] offset:128
	v_mul_f32_e32 v181, v62, v226
	v_cvt_pk_bf16_f32 v181, v181, v181
	global_store_short v240, v181, s[22:23] offset:192
	v_mul_f32_e32 v182, v78, v226
	v_cvt_pk_bf16_f32 v182, v182, v182
	global_store_short v240, v182, s[22:23] offset:256
	v_mul_f32_e32 v183, v94, v226
	v_cvt_pk_bf16_f32 v183, v183, v183
	global_store_short v240, v183, s[22:23] offset:320
	v_mul_f32_e32 v184, v112, v226
	v_cvt_pk_bf16_f32 v184, v184, v184
	global_store_short v240, v184, s[22:23] offset:384
	v_mul_f32_e32 v185, v128, v226
	v_cvt_pk_bf16_f32 v185, v185, v185
	global_store_short v240, v185, s[22:23] offset:448
	v_add_u32_e32 v240, 0x36000, v241
	v_mul_f32_e32 v186, v15, v227
	v_cvt_pk_bf16_f32 v186, v186, v186
	global_store_short v240, v186, s[22:23]
	v_mul_f32_e32 v187, v31, v227
	v_cvt_pk_bf16_f32 v187, v187, v187
	global_store_short v240, v187, s[22:23] offset:64
	v_mul_f32_e32 v188, v47, v227
	v_cvt_pk_bf16_f32 v188, v188, v188
	global_store_short v240, v188, s[22:23] offset:128
	v_mul_f32_e32 v189, v63, v227
	v_cvt_pk_bf16_f32 v189, v189, v189
	global_store_short v240, v189, s[22:23] offset:192
	v_mul_f32_e32 v190, v79, v227
	v_cvt_pk_bf16_f32 v190, v190, v190
	global_store_short v240, v190, s[22:23] offset:256
	v_mul_f32_e32 v191, v95, v227
	v_cvt_pk_bf16_f32 v191, v191, v191
	global_store_short v240, v191, s[22:23] offset:320
	v_mul_f32_e32 v192, v113, v227
	v_cvt_pk_bf16_f32 v192, v192, v192
	global_store_short v240, v192, s[22:23] offset:384
	v_mul_f32_e32 v193, v129, v227
	v_cvt_pk_bf16_f32 v193, v193, v193
	global_store_short v240, v193, s[22:23] offset:448
	s_waitcnt lgkmcnt(0)
	s_barrier
	s_cmpk_lt_u32 s0, 0x320
	s_cbranch_scc1 .Lam_done
	s_bitcmp1_b32 s0, 0
	s_cbranch_scc1 .Lam_done
	s_add_i32 s0, s0, 1
	s_branch .Lam_unit
